# baseline (speedup 1.0000x reference)
; #define MFMA16(a, b, c) __builtin_amdgcn_mfma_f32_16x16x32_bf16(a, b, c, 0, 0, 0)
; template <int DH, int MODE>
; __device__ void attn_item(const Params& p, int layer, int b, int blk, int head, char* smem) {
;     ...
;     {
;       char* kd_ = smem + (kc >> 2) * 4096 + kkey * 64 + (kc & 3) * 16;
;       *reinterpret_cast<uint4*>(kd_) = kr0;
;       *reinterpret_cast<uint4*>(kd_ + (2048 / DH) * 64) = kr1;
;       if (KCH > 2) {
;         *reinterpret_cast<uint4*>(kd_ + (2 * 2048 / DH) * 64) = kr2;
;         *reinterpret_cast<uint4*>(kd_ + (3 * 2048 / DH) * 64) = kr3;
;       }
;     }
;     __syncthreads();
;     if (!wskip) {
;       f32x4 s[2][4];
; #pragma unroll
;       for (int m = 0; m < 2; ++m)
; #pragma unroll
;         for (int n = 0; n < 4; ++n) s[m][n] = f32x4{0.f, 0.f, 0.f, 0.f};
; #pragma unroll
;       for (int ks = 0; ks < NKS; ++ks)
; #pragma unroll
;         for (int n = 0; n < 4; ++n) {
;           bf16x8 bfr = *reinterpret_cast<const bf16x8*>(smem + ks * 4096 + (n * 16 + fr) * 64 + fq * 16);
; #pragma unroll
;           for (int m = 0; m < 2; ++m) s[m][n] = MFMA16(bfr, qf[m][ks], s[m][n]);
;         }
; #pragma unroll
;       for (int m = 0; m < 2; ++m)
; #pragma unroll
;         for (int n = 0; n < 4; ++n)
;           *reinterpret_cast<float4*>(Sf + (wid * 32 + m * 16 + fr) * SSTR + n * 16 + fq * 4) =
;               make_float4(s[m][n][0] * scale, s[m][n][1] * scale, s[m][n][2] * scale, s[m][n][3] * scale);
;     }
.LBB0_200:
	s_and_b64 vcc, exec, s[50:51]
	s_cbranch_vccz .LBB0_212
	s_sub_i32 s8, s82, s84
	s_lshl_b32 s8, s8, 6
	v_cmp_lt_i32_e64 s[8:9], s8, v165
	s_waitcnt vmcnt(1)
	ds_write_b128 v169, v[112:115]
	s_waitcnt vmcnt(5)
	ds_write_b128 v169, v[120:123] offset:1024
	s_waitcnt vmcnt(4)
	ds_write_b128 v169, v[116:119] offset:2048
	s_waitcnt vmcnt(2)
	ds_write_b128 v169, v[124:127] offset:3072
	s_waitcnt lgkmcnt(0)
	s_barrier
	s_and_saveexec_b64 s[50:51], s[8:9]
	s_cbranch_execz .LBB0_203
	ds_read_b128 v[184:187], v128
	ds_read_b128 v[188:191], v128 offset:1024
	ds_read_b128 v[192:195], v128 offset:2048
	ds_read_b128 v[196:199], v128 offset:3072
	ds_read_b128 v[200:203], v128 offset:4096
	ds_read_b128 v[204:207], v128 offset:5120
	ds_read_b128 v[208:211], v128 offset:6144
	ds_read_b128 v[212:215], v128 offset:7168
	ds_read_b128 v[216:219], v128 offset:8192
	ds_read_b128 v[220:223], v128 offset:9216
	ds_read_b128 v[224:227], v128 offset:10240
	ds_read_b128 v[228:231], v128 offset:11264
	s_waitcnt lgkmcnt(11)
	v_mfma_f32_16x16x32_bf16 v[120:123], v[184:187], v[92:95], 0
	v_mfma_f32_16x16x32_bf16 v[112:115], v[184:187], v[76:79], 0
	ds_read_b128 v[184:187], v128 offset:12288
	s_waitcnt lgkmcnt(11)
	v_mfma_f32_16x16x32_bf16 v[124:127], v[188:191], v[92:95], 0
	v_mfma_f32_16x16x32_bf16 v[116:119], v[188:191], v[76:79], 0
	ds_read_b128 v[188:191], v128 offset:13312
	s_waitcnt lgkmcnt(9)
	v_mfma_f32_16x16x32_bf16 v[120:123], v[200:203], v[0:3], v[120:123]
	v_mfma_f32_16x16x32_bf16 v[112:115], v[200:203], v[80:83], v[112:115]
	s_waitcnt lgkmcnt(8)
	v_mfma_f32_16x16x32_bf16 v[124:127], v[204:207], v[0:3], v[124:127]
	v_mfma_f32_16x16x32_bf16 v[116:119], v[204:207], v[80:83], v[116:119]
	v_mfma_f32_16x16x32_bf16 v[176:179], v[192:195], v[92:95], 0
	v_mfma_f32_16x16x32_bf16 v[146:149], v[192:195], v[76:79], 0
	ds_read_b128 v[192:195], v128 offset:14336
	v_mfma_f32_16x16x32_bf16 v[180:183], v[196:199], v[92:95], 0
	v_mfma_f32_16x16x32_bf16 v[150:153], v[196:199], v[76:79], 0
	ds_read_b128 v[196:199], v128 offset:15360
	s_waitcnt lgkmcnt(9)
	v_mfma_f32_16x16x32_bf16 v[176:179], v[208:211], v[0:3], v[176:179]
	v_mfma_f32_16x16x32_bf16 v[146:149], v[208:211], v[80:83], v[146:149]
	s_waitcnt lgkmcnt(8)
	v_mfma_f32_16x16x32_bf16 v[180:183], v[212:215], v[0:3], v[180:183]
	v_mfma_f32_16x16x32_bf16 v[150:153], v[212:215], v[80:83], v[150:153]
	s_waitcnt lgkmcnt(7)
	v_mfma_f32_16x16x32_bf16 v[120:123], v[216:219], v[4:7], v[120:123]
	v_mfma_f32_16x16x32_bf16 v[112:115], v[216:219], v[84:87], v[112:115]
	s_waitcnt lgkmcnt(6)
	v_mfma_f32_16x16x32_bf16 v[124:127], v[220:223], v[4:7], v[124:127]
	v_mfma_f32_16x16x32_bf16 v[116:119], v[220:223], v[84:87], v[116:119]
	s_waitcnt lgkmcnt(5)
	v_mfma_f32_16x16x32_bf16 v[176:179], v[224:227], v[4:7], v[176:179]
	v_mfma_f32_16x16x32_bf16 v[146:149], v[224:227], v[84:87], v[146:149]
	s_waitcnt lgkmcnt(3)
	v_mfma_f32_16x16x32_bf16 v[120:123], v[184:187], v[8:11], v[120:123]
	s_nop 7
	v_pk_mul_f32 v[120:121], v[120:121], s[46:47] op_sel_hi:[1,0]
	v_mfma_f32_16x16x32_bf16 v[112:115], v[184:187], v[88:91], v[112:115]
	v_mul_f32_e64 v122, v122, s46
	v_mul_f32_e64 v123, v123, s46
	v_mfma_f32_16x16x32_bf16 v[180:183], v[228:231], v[4:7], v[180:183]
	v_mfma_f32_16x16x32_bf16 v[150:153], v[228:231], v[84:87], v[150:153]
	s_nop 0
	s_nop 2
	v_pk_mul_f32 v[112:113], v[112:113], s[46:47] op_sel_hi:[1,0]
	v_pk_mul_f32 v[114:115], v[114:115], s[46:47] op_sel_hi:[1,0]
	ds_write_b128 v170, v[120:123] offset:16384
	s_waitcnt lgkmcnt(3)
	v_mfma_f32_16x16x32_bf16 v[120:123], v[188:191], v[8:11], v[124:127]
	ds_write_b128 v170, v[112:115] offset:20736
	v_mfma_f32_16x16x32_bf16 v[112:115], v[188:191], v[88:91], v[116:119]
	s_nop 5
	v_mul_f32_e64 v120, v120, s46
	v_mul_f32_e64 v121, v121, s46
	v_pk_mul_f32 v[122:123], v[122:123], s[46:47] op_sel_hi:[1,0]
	v_pk_mul_f32 v[112:113], v[112:113], s[46:47] op_sel_hi:[1,0]
	v_pk_mul_f32 v[114:115], v[114:115], s[46:47] op_sel_hi:[1,0]
	ds_write_b128 v170, v[120:123] offset:16448
	s_waitcnt lgkmcnt(4)
	v_mfma_f32_16x16x32_bf16 v[120:123], v[192:195], v[8:11], v[176:179]
	ds_write_b128 v170, v[112:115] offset:20800
	v_mfma_f32_16x16x32_bf16 v[112:115], v[192:195], v[88:91], v[146:149]
	s_nop 5
	v_mul_f32_e64 v120, v120, s46
	v_mul_f32_e64 v121, v121, s46
	v_pk_mul_f32 v[122:123], v[122:123], s[46:47] op_sel_hi:[1,0]
	v_pk_mul_f32 v[112:113], v[112:113], s[46:47] op_sel_hi:[1,0]
	v_pk_mul_f32 v[114:115], v[114:115], s[46:47] op_sel_hi:[1,0]
	ds_write_b128 v170, v[120:123] offset:16512
	s_waitcnt lgkmcnt(5)
	v_mfma_f32_16x16x32_bf16 v[120:123], v[196:199], v[8:11], v[180:183]
	ds_write_b128 v170, v[112:115] offset:20864
	v_mfma_f32_16x16x32_bf16 v[112:115], v[196:199], v[88:91], v[150:153]
	s_nop 5
	v_mul_f32_e64 v120, v120, s46
	v_mul_f32_e64 v121, v121, s46
	v_pk_mul_f32 v[122:123], v[122:123], s[46:47] op_sel_hi:[1,0]
	v_pk_mul_f32 v[112:113], v[112:113], s[46:47] op_sel_hi:[1,0]
	v_pk_mul_f32 v[114:115], v[114:115], s[46:47] op_sel_hi:[1,0]
	ds_write_b128 v170, v[120:123] offset:16576
	ds_write_b128 v170, v[112:115] offset:20928

; #define MFMA16(a, b, c) __builtin_amdgcn_mfma_f32_16x16x32_bf16(a, b, c, 0, 0, 0)
; template <int DH, int MODE>
; __device__ void attn_item(const Params& p, int layer, int b, int blk, int head, char* smem) {
;     ...
;     {
;       char* kd_ = smem + (kc >> 2) * 4096 + kkey * 64 + (kc & 3) * 16;
;       *reinterpret_cast<uint4*>(kd_) = kr0;
;       *reinterpret_cast<uint4*>(kd_ + (2048 / DH) * 64) = kr1;
;       if (KCH > 2) {
;         *reinterpret_cast<uint4*>(kd_ + (2 * 2048 / DH) * 64) = kr2;
;         *reinterpret_cast<uint4*>(kd_ + (3 * 2048 / DH) * 64) = kr3;
;       }
;     }
;     __syncthreads();
;     if (!wskip) {
;       f32x4 s[2][4];
; #pragma unroll
;       for (int m = 0; m < 2; ++m)
; #pragma unroll
;         for (int n = 0; n < 4; ++n) s[m][n] = f32x4{0.f, 0.f, 0.f, 0.f};
; #pragma unroll
;       for (int ks = 0; ks < NKS; ++ks)
; #pragma unroll
;         for (int n = 0; n < 4; ++n) {
;           bf16x8 bfr = *reinterpret_cast<const bf16x8*>(smem + ks * 4096 + (n * 16 + fr) * 64 + fq * 16);
; #pragma unroll
;           for (int m = 0; m < 2; ++m) s[m][n] = MFMA16(bfr, qf[m][ks], s[m][n]);
;         }
; #pragma unroll
;       for (int m = 0; m < 2; ++m)
; #pragma unroll
;         for (int n = 0; n < 4; ++n)
;           *reinterpret_cast<float4*>(Sf + (wid * 32 + m * 16 + fr) * SSTR + n * 16 + fq * 4) =
;               make_float4(s[m][n][0] * scale, s[m][n][1] * scale, s[m][n][2] * scale, s[m][n][3] * scale);
;     }
.LBB0_521:
	s_and_b64 vcc, exec, s[52:53]
	s_cbranch_vccz .LBB0_533
	s_sub_i32 s16, s85, s87
	s_lshl_b32 s16, s16, 6
	v_cmp_lt_i32_e64 s[16:17], s16, v165
	s_waitcnt vmcnt(1)
	ds_write_b128 v169, v[112:115]
	s_waitcnt vmcnt(5)
	ds_write_b128 v169, v[120:123] offset:1024
	s_waitcnt vmcnt(4)
	ds_write_b128 v169, v[116:119] offset:2048
	s_waitcnt vmcnt(2)
	ds_write_b128 v169, v[124:127] offset:3072
	s_waitcnt lgkmcnt(0)
	s_barrier
	s_and_saveexec_b64 s[52:53], s[16:17]
	s_cbranch_execz .LBB0_524
	ds_read_b128 v[184:187], v128
	ds_read_b128 v[188:191], v128 offset:1024
	ds_read_b128 v[192:195], v128 offset:2048
	ds_read_b128 v[196:199], v128 offset:3072
	ds_read_b128 v[200:203], v128 offset:4096
	ds_read_b128 v[204:207], v128 offset:5120
	ds_read_b128 v[208:211], v128 offset:6144
	ds_read_b128 v[212:215], v128 offset:7168
	ds_read_b128 v[216:219], v128 offset:8192
	ds_read_b128 v[220:223], v128 offset:9216
	ds_read_b128 v[224:227], v128 offset:10240
	ds_read_b128 v[228:231], v128 offset:11264
	s_waitcnt lgkmcnt(11)
	v_mfma_f32_16x16x32_bf16 v[120:123], v[184:187], v[92:95], 0
	v_mfma_f32_16x16x32_bf16 v[112:115], v[184:187], v[76:79], 0
	ds_read_b128 v[184:187], v128 offset:12288
	s_waitcnt lgkmcnt(11)
	v_mfma_f32_16x16x32_bf16 v[124:127], v[188:191], v[92:95], 0
	v_mfma_f32_16x16x32_bf16 v[116:119], v[188:191], v[76:79], 0
	ds_read_b128 v[188:191], v128 offset:13312
	s_waitcnt lgkmcnt(9)
	v_mfma_f32_16x16x32_bf16 v[120:123], v[200:203], v[0:3], v[120:123]
	v_mfma_f32_16x16x32_bf16 v[112:115], v[200:203], v[80:83], v[112:115]
	s_waitcnt lgkmcnt(8)
	v_mfma_f32_16x16x32_bf16 v[124:127], v[204:207], v[0:3], v[124:127]
	v_mfma_f32_16x16x32_bf16 v[116:119], v[204:207], v[80:83], v[116:119]
	v_mfma_f32_16x16x32_bf16 v[176:179], v[192:195], v[92:95], 0
	v_mfma_f32_16x16x32_bf16 v[146:149], v[192:195], v[76:79], 0
	ds_read_b128 v[192:195], v128 offset:14336
	v_mfma_f32_16x16x32_bf16 v[180:183], v[196:199], v[92:95], 0
	v_mfma_f32_16x16x32_bf16 v[150:153], v[196:199], v[76:79], 0
	ds_read_b128 v[196:199], v128 offset:15360
	s_waitcnt lgkmcnt(9)
	v_mfma_f32_16x16x32_bf16 v[176:179], v[208:211], v[0:3], v[176:179]
	v_mfma_f32_16x16x32_bf16 v[146:149], v[208:211], v[80:83], v[146:149]
	s_waitcnt lgkmcnt(8)
	v_mfma_f32_16x16x32_bf16 v[180:183], v[212:215], v[0:3], v[180:183]
	v_mfma_f32_16x16x32_bf16 v[150:153], v[212:215], v[80:83], v[150:153]
	s_waitcnt lgkmcnt(7)
	v_mfma_f32_16x16x32_bf16 v[120:123], v[216:219], v[4:7], v[120:123]
	v_mfma_f32_16x16x32_bf16 v[112:115], v[216:219], v[84:87], v[112:115]
	s_waitcnt lgkmcnt(6)
	v_mfma_f32_16x16x32_bf16 v[124:127], v[220:223], v[4:7], v[124:127]
	v_mfma_f32_16x16x32_bf16 v[116:119], v[220:223], v[84:87], v[116:119]
	s_waitcnt lgkmcnt(5)
	v_mfma_f32_16x16x32_bf16 v[176:179], v[224:227], v[4:7], v[176:179]
	v_mfma_f32_16x16x32_bf16 v[146:149], v[224:227], v[84:87], v[146:149]
	s_waitcnt lgkmcnt(3)
	v_mfma_f32_16x16x32_bf16 v[120:123], v[184:187], v[8:11], v[120:123]
	s_nop 7
	v_pk_mul_f32 v[120:121], v[120:121], s[48:49] op_sel_hi:[1,0]
	v_mfma_f32_16x16x32_bf16 v[112:115], v[184:187], v[88:91], v[112:115]
	v_mul_f32_e64 v122, v122, s48
	v_mul_f32_e64 v123, v123, s48
	v_mfma_f32_16x16x32_bf16 v[180:183], v[228:231], v[4:7], v[180:183]
	v_mfma_f32_16x16x32_bf16 v[150:153], v[228:231], v[84:87], v[150:153]
	s_nop 0
	s_nop 2
	v_pk_mul_f32 v[112:113], v[112:113], s[48:49] op_sel_hi:[1,0]
	v_pk_mul_f32 v[114:115], v[114:115], s[48:49] op_sel_hi:[1,0]
	ds_write_b128 v170, v[120:123] offset:16384
	s_waitcnt lgkmcnt(3)
	v_mfma_f32_16x16x32_bf16 v[120:123], v[188:191], v[8:11], v[124:127]
	ds_write_b128 v170, v[112:115] offset:20736
	v_mfma_f32_16x16x32_bf16 v[112:115], v[188:191], v[88:91], v[116:119]
	s_nop 5
	v_mul_f32_e64 v120, v120, s48
	v_mul_f32_e64 v121, v121, s48
	v_pk_mul_f32 v[122:123], v[122:123], s[48:49] op_sel_hi:[1,0]
	v_pk_mul_f32 v[112:113], v[112:113], s[48:49] op_sel_hi:[1,0]
	v_pk_mul_f32 v[114:115], v[114:115], s[48:49] op_sel_hi:[1,0]
	ds_write_b128 v170, v[120:123] offset:16448
	s_waitcnt lgkmcnt(4)
	v_mfma_f32_16x16x32_bf16 v[120:123], v[192:195], v[8:11], v[176:179]
	ds_write_b128 v170, v[112:115] offset:20800
	v_mfma_f32_16x16x32_bf16 v[112:115], v[192:195], v[88:91], v[146:149]
	s_nop 5
	v_mul_f32_e64 v120, v120, s48
	v_mul_f32_e64 v121, v121, s48
	v_pk_mul_f32 v[122:123], v[122:123], s[48:49] op_sel_hi:[1,0]
	v_pk_mul_f32 v[112:113], v[112:113], s[48:49] op_sel_hi:[1,0]
	v_pk_mul_f32 v[114:115], v[114:115], s[48:49] op_sel_hi:[1,0]
	ds_write_b128 v170, v[120:123] offset:16512
	s_waitcnt lgkmcnt(5)
	v_mfma_f32_16x16x32_bf16 v[120:123], v[196:199], v[8:11], v[180:183]
	ds_write_b128 v170, v[112:115] offset:20864
	v_mfma_f32_16x16x32_bf16 v[112:115], v[196:199], v[88:91], v[150:153]
	s_nop 5
	v_mul_f32_e64 v120, v120, s48
	v_mul_f32_e64 v121, v121, s48
	v_pk_mul_f32 v[122:123], v[122:123], s[48:49] op_sel_hi:[1,0]
	v_pk_mul_f32 v[112:113], v[112:113], s[48:49] op_sel_hi:[1,0]
	v_pk_mul_f32 v[114:115], v[114:115], s[48:49] op_sel_hi:[1,0]
	ds_write_b128 v170, v[120:123] offset:16576
	ds_write_b128 v170, v[112:115] offset:20928

; #define MFMA16(a, b, c) __builtin_amdgcn_mfma_f32_16x16x32_bf16(a, b, c, 0, 0, 0)
; template <int DH, int MODE>
; __device__ void attn_item(const Params& p, int layer, int b, int blk, int head, char* smem) {
;     ...
;     {
;       char* kd_ = smem + (kc >> 2) * 4096 + kkey * 64 + (kc & 3) * 16;
;       *reinterpret_cast<uint4*>(kd_) = kr0;
;       *reinterpret_cast<uint4*>(kd_ + (2048 / DH) * 64) = kr1;
;       if (KCH > 2) {
;         *reinterpret_cast<uint4*>(kd_ + (2 * 2048 / DH) * 64) = kr2;
;         *reinterpret_cast<uint4*>(kd_ + (3 * 2048 / DH) * 64) = kr3;
;       }
;     }
;     __syncthreads();
;     if (!wskip) {
;       f32x4 s[2][4];
; #pragma unroll
;       for (int m = 0; m < 2; ++m)
; #pragma unroll
;         for (int n = 0; n < 4; ++n) s[m][n] = f32x4{0.f, 0.f, 0.f, 0.f};
; #pragma unroll
;       for (int ks = 0; ks < NKS; ++ks)
; #pragma unroll
;         for (int n = 0; n < 4; ++n) {
;           bf16x8 bfr = *reinterpret_cast<const bf16x8*>(smem + ks * 4096 + (n * 16 + fr) * 64 + fq * 16);
; #pragma unroll
;           for (int m = 0; m < 2; ++m) s[m][n] = MFMA16(bfr, qf[m][ks], s[m][n]);
;         }
; #pragma unroll
;       for (int m = 0; m < 2; ++m)
; #pragma unroll
;         for (int n = 0; n < 4; ++n)
;           *reinterpret_cast<float4*>(Sf + (wid * 32 + m * 16 + fr) * SSTR + n * 16 + fq * 4) =
;               make_float4(s[m][n][0] * scale, s[m][n][1] * scale, s[m][n][2] * scale, s[m][n][3] * scale);
;     }
.LBB0_842:
	s_and_b64 vcc, exec, s[50:51]
	s_cbranch_vccz .LBB0_854
	s_sub_i32 s16, s85, s87
	s_lshl_b32 s16, s16, 6
	v_cmp_lt_i32_e64 s[16:17], s16, v165
	s_waitcnt vmcnt(1)
	ds_write_b128 v169, v[112:115]
	s_waitcnt vmcnt(5)
	ds_write_b128 v169, v[120:123] offset:1024
	s_waitcnt vmcnt(4)
	ds_write_b128 v169, v[116:119] offset:2048
	s_waitcnt vmcnt(2)
	ds_write_b128 v169, v[124:127] offset:3072
	s_waitcnt lgkmcnt(0)
	s_barrier
	s_and_saveexec_b64 s[50:51], s[16:17]
	s_cbranch_execz .LBB0_845
	ds_read_b128 v[184:187], v128
	ds_read_b128 v[188:191], v128 offset:1024
	ds_read_b128 v[192:195], v128 offset:2048
	ds_read_b128 v[196:199], v128 offset:3072
	ds_read_b128 v[200:203], v128 offset:4096
	ds_read_b128 v[204:207], v128 offset:5120
	ds_read_b128 v[208:211], v128 offset:6144
	ds_read_b128 v[212:215], v128 offset:7168
	ds_read_b128 v[216:219], v128 offset:8192
	ds_read_b128 v[220:223], v128 offset:9216
	ds_read_b128 v[224:227], v128 offset:10240
	ds_read_b128 v[228:231], v128 offset:11264
	s_waitcnt lgkmcnt(11)
	v_mfma_f32_16x16x32_bf16 v[120:123], v[184:187], v[92:95], 0
	v_mfma_f32_16x16x32_bf16 v[112:115], v[184:187], v[76:79], 0
	ds_read_b128 v[184:187], v128 offset:12288
	s_waitcnt lgkmcnt(11)
	v_mfma_f32_16x16x32_bf16 v[124:127], v[188:191], v[92:95], 0
	v_mfma_f32_16x16x32_bf16 v[116:119], v[188:191], v[76:79], 0
	ds_read_b128 v[188:191], v128 offset:13312
	s_waitcnt lgkmcnt(9)
	v_mfma_f32_16x16x32_bf16 v[120:123], v[200:203], v[0:3], v[120:123]
	v_mfma_f32_16x16x32_bf16 v[112:115], v[200:203], v[80:83], v[112:115]
	s_waitcnt lgkmcnt(8)
	v_mfma_f32_16x16x32_bf16 v[124:127], v[204:207], v[0:3], v[124:127]
	v_mfma_f32_16x16x32_bf16 v[116:119], v[204:207], v[80:83], v[116:119]
	v_mfma_f32_16x16x32_bf16 v[176:179], v[192:195], v[92:95], 0
	v_mfma_f32_16x16x32_bf16 v[146:149], v[192:195], v[76:79], 0
	ds_read_b128 v[192:195], v128 offset:14336
	v_mfma_f32_16x16x32_bf16 v[180:183], v[196:199], v[92:95], 0
	v_mfma_f32_16x16x32_bf16 v[150:153], v[196:199], v[76:79], 0
	ds_read_b128 v[196:199], v128 offset:15360
	s_waitcnt lgkmcnt(9)
	v_mfma_f32_16x16x32_bf16 v[176:179], v[208:211], v[0:3], v[176:179]
	v_mfma_f32_16x16x32_bf16 v[146:149], v[208:211], v[80:83], v[146:149]
	s_waitcnt lgkmcnt(8)
	v_mfma_f32_16x16x32_bf16 v[180:183], v[212:215], v[0:3], v[180:183]
	v_mfma_f32_16x16x32_bf16 v[150:153], v[212:215], v[80:83], v[150:153]
	s_waitcnt lgkmcnt(7)
	v_mfma_f32_16x16x32_bf16 v[120:123], v[216:219], v[4:7], v[120:123]
	v_mfma_f32_16x16x32_bf16 v[112:115], v[216:219], v[84:87], v[112:115]
	s_waitcnt lgkmcnt(6)
	v_mfma_f32_16x16x32_bf16 v[124:127], v[220:223], v[4:7], v[124:127]
	v_mfma_f32_16x16x32_bf16 v[116:119], v[220:223], v[84:87], v[116:119]
	s_waitcnt lgkmcnt(5)
	v_mfma_f32_16x16x32_bf16 v[176:179], v[224:227], v[4:7], v[176:179]
	v_mfma_f32_16x16x32_bf16 v[146:149], v[224:227], v[84:87], v[146:149]
	s_waitcnt lgkmcnt(3)
	v_mfma_f32_16x16x32_bf16 v[120:123], v[184:187], v[8:11], v[120:123]
	s_nop 7
	v_pk_mul_f32 v[120:121], v[120:121], s[46:47] op_sel_hi:[1,0]
	v_mfma_f32_16x16x32_bf16 v[112:115], v[184:187], v[88:91], v[112:115]
	v_mul_f32_e64 v122, v122, s46
	v_mul_f32_e64 v123, v123, s46
	v_mfma_f32_16x16x32_bf16 v[180:183], v[228:231], v[4:7], v[180:183]
	v_mfma_f32_16x16x32_bf16 v[150:153], v[228:231], v[84:87], v[150:153]
	s_nop 0
	s_nop 2
	v_pk_mul_f32 v[112:113], v[112:113], s[46:47] op_sel_hi:[1,0]
	v_pk_mul_f32 v[114:115], v[114:115], s[46:47] op_sel_hi:[1,0]
	ds_write_b128 v170, v[120:123] offset:16384
	s_waitcnt lgkmcnt(3)
	v_mfma_f32_16x16x32_bf16 v[120:123], v[188:191], v[8:11], v[124:127]
	ds_write_b128 v170, v[112:115] offset:20736
	v_mfma_f32_16x16x32_bf16 v[112:115], v[188:191], v[88:91], v[116:119]
	s_nop 5
	v_mul_f32_e64 v120, v120, s46
	v_mul_f32_e64 v121, v121, s46
	v_pk_mul_f32 v[122:123], v[122:123], s[46:47] op_sel_hi:[1,0]
	v_pk_mul_f32 v[112:113], v[112:113], s[46:47] op_sel_hi:[1,0]
	v_pk_mul_f32 v[114:115], v[114:115], s[46:47] op_sel_hi:[1,0]
	ds_write_b128 v170, v[120:123] offset:16448
	s_waitcnt lgkmcnt(4)
	v_mfma_f32_16x16x32_bf16 v[120:123], v[192:195], v[8:11], v[176:179]
	ds_write_b128 v170, v[112:115] offset:20800
	v_mfma_f32_16x16x32_bf16 v[112:115], v[192:195], v[88:91], v[146:149]
	s_nop 5
	v_mul_f32_e64 v120, v120, s46
	v_mul_f32_e64 v121, v121, s46
	v_pk_mul_f32 v[122:123], v[122:123], s[46:47] op_sel_hi:[1,0]
	v_pk_mul_f32 v[112:113], v[112:113], s[46:47] op_sel_hi:[1,0]
	v_pk_mul_f32 v[114:115], v[114:115], s[46:47] op_sel_hi:[1,0]
	ds_write_b128 v170, v[120:123] offset:16512
	s_waitcnt lgkmcnt(5)
	v_mfma_f32_16x16x32_bf16 v[120:123], v[196:199], v[8:11], v[180:183]
	ds_write_b128 v170, v[112:115] offset:20864
	v_mfma_f32_16x16x32_bf16 v[112:115], v[196:199], v[88:91], v[150:153]
	s_nop 5
	v_mul_f32_e64 v120, v120, s46
	v_mul_f32_e64 v121, v121, s46
	v_pk_mul_f32 v[122:123], v[122:123], s[46:47] op_sel_hi:[1,0]
	v_pk_mul_f32 v[112:113], v[112:113], s[46:47] op_sel_hi:[1,0]
	v_pk_mul_f32 v[114:115], v[114:115], s[46:47] op_sel_hi:[1,0]
	ds_write_b128 v170, v[120:123] offset:16576
	ds_write_b128 v170, v[112:115] offset:20928

; #define MFMA16(a, b, c) __builtin_amdgcn_mfma_f32_16x16x32_bf16(a, b, c, 0, 0, 0)
; template <int DH, int MODE>
; __device__ void attn_item(const Params& p, int layer, int b, int blk, int head, char* smem) {
;     ...
;     {
;       char* kd_ = smem + (kc >> 2) * 4096 + kkey * 64 + (kc & 3) * 16;
;       *reinterpret_cast<uint4*>(kd_) = kr0;
;       *reinterpret_cast<uint4*>(kd_ + (2048 / DH) * 64) = kr1;
;       if (KCH > 2) {
;         *reinterpret_cast<uint4*>(kd_ + (2 * 2048 / DH) * 64) = kr2;
;         *reinterpret_cast<uint4*>(kd_ + (3 * 2048 / DH) * 64) = kr3;
;       }
;     }
;     __syncthreads();
;     if (!wskip) {
;       f32x4 s[2][4];
; #pragma unroll
;       for (int m = 0; m < 2; ++m)
; #pragma unroll
;         for (int n = 0; n < 4; ++n) s[m][n] = f32x4{0.f, 0.f, 0.f, 0.f};
; #pragma unroll
;       for (int ks = 0; ks < NKS; ++ks)
; #pragma unroll
;         for (int n = 0; n < 4; ++n) {
;           bf16x8 bfr = *reinterpret_cast<const bf16x8*>(smem + ks * 4096 + (n * 16 + fr) * 64 + fq * 16);
; #pragma unroll
;           for (int m = 0; m < 2; ++m) s[m][n] = MFMA16(bfr, qf[m][ks], s[m][n]);
;         }
; #pragma unroll
;       for (int m = 0; m < 2; ++m)
; #pragma unroll
;         for (int n = 0; n < 4; ++n)
;           *reinterpret_cast<float4*>(Sf + (wid * 32 + m * 16 + fr) * SSTR + n * 16 + fq * 4) =
;               make_float4(s[m][n][0] * scale, s[m][n][1] * scale, s[m][n][2] * scale, s[m][n][3] * scale);
;     }
.LBB0_1163:
	s_and_b64 vcc, exec, s[44:45]
	s_cbranch_vccz .LBB0_1175
	s_sub_i32 s10, s78, s80
	s_lshl_b32 s10, s10, 6
	v_cmp_lt_i32_e64 s[10:11], s10, v165
	s_waitcnt vmcnt(1)
	ds_write_b128 v169, v[112:115]
	s_waitcnt vmcnt(5)
	ds_write_b128 v169, v[120:123] offset:1024
	s_waitcnt vmcnt(4)
	ds_write_b128 v169, v[116:119] offset:2048
	s_waitcnt vmcnt(2)
	ds_write_b128 v169, v[124:127] offset:3072
	s_waitcnt lgkmcnt(0)
	s_barrier
	s_and_saveexec_b64 s[44:45], s[10:11]
	s_cbranch_execz .LBB0_1166
	ds_read_b128 v[184:187], v128
	ds_read_b128 v[188:191], v128 offset:1024
	ds_read_b128 v[192:195], v128 offset:2048
	ds_read_b128 v[196:199], v128 offset:3072
	ds_read_b128 v[200:203], v128 offset:4096
	ds_read_b128 v[204:207], v128 offset:5120
	ds_read_b128 v[208:211], v128 offset:6144
	ds_read_b128 v[212:215], v128 offset:7168
	ds_read_b128 v[216:219], v128 offset:8192
	ds_read_b128 v[220:223], v128 offset:9216
	ds_read_b128 v[224:227], v128 offset:10240
	ds_read_b128 v[228:231], v128 offset:11264
	s_waitcnt lgkmcnt(11)
	v_mfma_f32_16x16x32_bf16 v[120:123], v[184:187], v[92:95], 0
	v_mfma_f32_16x16x32_bf16 v[112:115], v[184:187], v[76:79], 0
	ds_read_b128 v[184:187], v128 offset:12288
	s_waitcnt lgkmcnt(11)
	v_mfma_f32_16x16x32_bf16 v[124:127], v[188:191], v[92:95], 0
	v_mfma_f32_16x16x32_bf16 v[116:119], v[188:191], v[76:79], 0
	ds_read_b128 v[188:191], v128 offset:13312
	s_waitcnt lgkmcnt(9)
	v_mfma_f32_16x16x32_bf16 v[120:123], v[200:203], v[0:3], v[120:123]
	v_mfma_f32_16x16x32_bf16 v[112:115], v[200:203], v[80:83], v[112:115]
	s_waitcnt lgkmcnt(8)
	v_mfma_f32_16x16x32_bf16 v[124:127], v[204:207], v[0:3], v[124:127]
	v_mfma_f32_16x16x32_bf16 v[116:119], v[204:207], v[80:83], v[116:119]
	v_mfma_f32_16x16x32_bf16 v[176:179], v[192:195], v[92:95], 0
	v_mfma_f32_16x16x32_bf16 v[146:149], v[192:195], v[76:79], 0
	ds_read_b128 v[192:195], v128 offset:14336
	v_mfma_f32_16x16x32_bf16 v[180:183], v[196:199], v[92:95], 0
	v_mfma_f32_16x16x32_bf16 v[150:153], v[196:199], v[76:79], 0
	ds_read_b128 v[196:199], v128 offset:15360
	s_waitcnt lgkmcnt(9)
	v_mfma_f32_16x16x32_bf16 v[176:179], v[208:211], v[0:3], v[176:179]
	v_mfma_f32_16x16x32_bf16 v[146:149], v[208:211], v[80:83], v[146:149]
	s_waitcnt lgkmcnt(8)
	v_mfma_f32_16x16x32_bf16 v[180:183], v[212:215], v[0:3], v[180:183]
	v_mfma_f32_16x16x32_bf16 v[150:153], v[212:215], v[80:83], v[150:153]
	s_waitcnt lgkmcnt(7)
	v_mfma_f32_16x16x32_bf16 v[120:123], v[216:219], v[4:7], v[120:123]
	v_mfma_f32_16x16x32_bf16 v[112:115], v[216:219], v[84:87], v[112:115]
	s_waitcnt lgkmcnt(6)
	v_mfma_f32_16x16x32_bf16 v[124:127], v[220:223], v[4:7], v[124:127]
	v_mfma_f32_16x16x32_bf16 v[116:119], v[220:223], v[84:87], v[116:119]
	s_waitcnt lgkmcnt(5)
	v_mfma_f32_16x16x32_bf16 v[176:179], v[224:227], v[4:7], v[176:179]
	v_mfma_f32_16x16x32_bf16 v[146:149], v[224:227], v[84:87], v[146:149]
	s_waitcnt lgkmcnt(3)
	v_mfma_f32_16x16x32_bf16 v[120:123], v[184:187], v[8:11], v[120:123]
	s_nop 7
	v_pk_mul_f32 v[120:121], v[120:121], s[40:41] op_sel_hi:[1,0]
	v_mfma_f32_16x16x32_bf16 v[112:115], v[184:187], v[88:91], v[112:115]
	v_mul_f32_e64 v122, v122, s40
	v_mul_f32_e64 v123, v123, s40
	v_mfma_f32_16x16x32_bf16 v[180:183], v[228:231], v[4:7], v[180:183]
	v_mfma_f32_16x16x32_bf16 v[150:153], v[228:231], v[84:87], v[150:153]
	s_nop 0
	s_nop 2
	v_pk_mul_f32 v[112:113], v[112:113], s[40:41] op_sel_hi:[1,0]
	v_pk_mul_f32 v[114:115], v[114:115], s[40:41] op_sel_hi:[1,0]
	ds_write_b128 v170, v[120:123] offset:16384
	s_waitcnt lgkmcnt(3)
	v_mfma_f32_16x16x32_bf16 v[120:123], v[188:191], v[8:11], v[124:127]
	ds_write_b128 v170, v[112:115] offset:20736
	v_mfma_f32_16x16x32_bf16 v[112:115], v[188:191], v[88:91], v[116:119]
	s_nop 5
	v_mul_f32_e64 v120, v120, s40
	v_mul_f32_e64 v121, v121, s40
	v_pk_mul_f32 v[122:123], v[122:123], s[40:41] op_sel_hi:[1,0]
	v_pk_mul_f32 v[112:113], v[112:113], s[40:41] op_sel_hi:[1,0]
	v_pk_mul_f32 v[114:115], v[114:115], s[40:41] op_sel_hi:[1,0]
	ds_write_b128 v170, v[120:123] offset:16448
	s_waitcnt lgkmcnt(4)
	v_mfma_f32_16x16x32_bf16 v[120:123], v[192:195], v[8:11], v[176:179]
	ds_write_b128 v170, v[112:115] offset:20800
	v_mfma_f32_16x16x32_bf16 v[112:115], v[192:195], v[88:91], v[146:149]
	s_nop 5
	v_mul_f32_e64 v120, v120, s40
	v_mul_f32_e64 v121, v121, s40
	v_pk_mul_f32 v[122:123], v[122:123], s[40:41] op_sel_hi:[1,0]
	v_pk_mul_f32 v[112:113], v[112:113], s[40:41] op_sel_hi:[1,0]
	v_pk_mul_f32 v[114:115], v[114:115], s[40:41] op_sel_hi:[1,0]
	ds_write_b128 v170, v[120:123] offset:16512
	s_waitcnt lgkmcnt(5)
	v_mfma_f32_16x16x32_bf16 v[120:123], v[196:199], v[8:11], v[180:183]
	ds_write_b128 v170, v[112:115] offset:20864
	v_mfma_f32_16x16x32_bf16 v[112:115], v[196:199], v[88:91], v[150:153]
	s_nop 5
	v_mul_f32_e64 v120, v120, s40
	v_mul_f32_e64 v121, v121, s40
	v_pk_mul_f32 v[122:123], v[122:123], s[40:41] op_sel_hi:[1,0]
	v_pk_mul_f32 v[112:113], v[112:113], s[40:41] op_sel_hi:[1,0]
	v_pk_mul_f32 v[114:115], v[114:115], s[40:41] op_sel_hi:[1,0]
	ds_write_b128 v170, v[120:123] offset:16576
	ds_write_b128 v170, v[112:115] offset:20928
